# attention loops: row-sum chains start from the first pair instead of adding to zero
# speedup vs baseline: 1.0036x; 1.0000x over previous
.LBB0_522:
	s_cmp_lt_u32 s15, s10
	s_cselect_b32 s4, 0, s10
	s_cselect_b32 s5, s40, s7
	s_lshl_b32 s4, s4, 5
	s_sub_i32 s4, s5, s4
	s_add_i32 s30, s21, s4
	s_add_i32 s4, s11, s15
	v_add_u32_e32 v66, s30, v189
	s_cmp_lt_u32 s4, s10
	v_ashrrev_i32_e32 v67, 31, v66
	s_cselect_b32 s4, 0, s10
	v_lshlrev_b64 v[66:67], 10, v[66:67]
	s_cselect_b32 s5, s40, s7
	s_lshl_b32 s4, s4, 5
	v_add_u32_e32 v228, 0xec00, v193
	v_add_u32_e32 v229, 0x4800, v192
	v_add_u32_e32 v230, 0x6c00, v192
	v_lshl_add_u64 v[66:67], v[178:179], 0, v[66:67]
	s_sub_i32 s4, s5, s4
	s_add_i32 s5, s33, s21
	s_waitcnt vmcnt(9)
	ds_write_b128 v191, v[130:133]
	s_waitcnt vmcnt(8)
	ds_write2_b64 v192, v[134:135], v[136:137] offset1:1
	s_waitcnt vmcnt(7)
	ds_write_b128 v191, v[142:145] offset:12800
	s_waitcnt vmcnt(6)
	ds_write2_b64 v228, v[138:139], v[140:141] offset1:1
	s_waitcnt vmcnt(5)
	ds_write_b128 v191, v[150:153] offset:25600
	s_waitcnt vmcnt(4)
	ds_write2_b64 v229, v[146:147], v[148:149] offset1:1
	s_waitcnt vmcnt(3)
	ds_write_b128 v191, v[158:161] offset:38400
	s_waitcnt vmcnt(2)
	ds_write2_b64 v230, v[154:155], v[156:157] offset1:1
	s_waitcnt vmcnt(1)
	ds_write_b128 v194, v[162:165] offset:256
	s_waitcnt vmcnt(0)
	ds_write_b128 v195, v[166:169] offset:256
	s_waitcnt lgkmcnt(0)
	s_barrier
	global_load_dwordx4 v[130:133], v[66:67], off
	v_lshl_add_u64 v[66:67], s[30:31], 1, v[180:181]
	s_add_i32 s30, s5, s4
	s_add_i32 s4, s4, s21
	global_load_dwordx4 v[134:137], v[66:67], off
	v_add_u32_e32 v66, s4, v201
	s_add_i32 s4, s18, s15
	s_cmp_lt_u32 s4, s10
	v_ashrrev_i32_e32 v67, 31, v66
	s_cselect_b32 s4, 0, s10
	v_lshlrev_b64 v[66:67], 10, v[66:67]
	s_cselect_b32 s5, s40, s7
	s_lshl_b32 s4, s4, 5
	v_lshl_add_u64 v[66:67], v[178:179], 0, v[66:67]
	s_sub_i32 s4, s5, s4
	s_add_i32 s5, s39, s21
	global_load_dwordx4 v[142:145], v[66:67], off
	v_lshl_add_u64 v[66:67], s[30:31], 1, v[180:181]
	s_add_i32 s30, s5, s4
	s_add_i32 s4, s4, s21
	global_load_dwordx4 v[138:141], v[66:67], off
	v_add_u32_e32 v66, s4, v199
	s_add_i32 s4, s19, s15
	s_cmp_lt_u32 s4, s10
	v_ashrrev_i32_e32 v67, 31, v66
	s_cselect_b32 s4, 0, s10
	v_lshlrev_b64 v[66:67], 10, v[66:67]
	s_cselect_b32 s5, s40, s7
	s_lshl_b32 s4, s4, 5
	v_lshl_add_u64 v[66:67], v[178:179], 0, v[66:67]
	s_sub_i32 s4, s5, s4
	s_add_i32 s5, s20, s21
	global_load_dwordx4 v[150:153], v[66:67], off
	v_lshl_add_u64 v[66:67], s[30:31], 1, v[180:181]
	s_add_i32 s30, s5, s4
	s_add_i32 s4, s4, s21
	global_load_dwordx4 v[146:149], v[66:67], off
	v_add_u32_e32 v66, s4, v200
	v_ashrrev_i32_e32 v67, 31, v66
	v_lshlrev_b64 v[66:67], 10, v[66:67]
	v_lshl_add_u64 v[66:67], v[178:179], 0, v[66:67]
	global_load_dwordx4 v[158:161], v[66:67], off
	v_lshl_add_u64 v[66:67], s[30:31], 1, v[180:181]
	v_cmp_gt_i32_e32 vcc, s10, v197
	v_mov_b32_e32 v68, s10
	global_load_dwordx4 v[154:157], v[66:67], off
	v_cndmask_b32_e64 v66, v68, 0, vcc
	v_mov_b32_e32 v69, s7
	v_mov_b32_e32 v70, s40
	v_cndmask_b32_e32 v67, v69, v70, vcc
	v_lshlrev_b32_e32 v66, 5, v66
	v_sub_u32_e32 v66, v67, v66
	v_add3_u32 v66, v198, s21, v66
	v_ashrrev_i32_e32 v67, 31, v66
	v_lshlrev_b64 v[66:67], 7, v[66:67]
	v_lshl_add_u64 v[66:67], v[182:183], 0, v[66:67]
	global_load_dwordx4 v[162:165], v[66:67], off
	v_add_u32_e32 v66, s18, v197
	v_cmp_gt_i32_e32 vcc, s10, v66
	v_mov_b32_e32 v0, v185
	v_mov_b32_e32 v235, v184
	v_cndmask_b32_e64 v66, v68, 0, vcc
	v_cndmask_b32_e32 v67, v69, v70, vcc
	v_lshlrev_b32_e32 v66, 5, v66
	v_sub_u32_e32 v66, v67, v66
	v_add3_u32 v66, v196, s21, v66
	v_ashrrev_i32_e32 v67, 31, v66
	v_lshlrev_b64 v[66:67], 7, v[66:67]
	v_lshl_add_u64 v[66:67], v[182:183], 0, v[66:67]
	global_load_dwordx4 v[166:169], v[66:67], off
	ds_read_b128 v[66:69], v190
	ds_read_b128 v[236:239], v190 offset:32
	s_waitcnt lgkmcnt(1)
	v_mfma_f32_32x32x16_bf16 v[66:81], v[66:69], v[118:121], 0
	v_add_u32_e32 v234, 0xc800, v227
	v_add_u32_e32 v231, 0xd800, v227
	s_add_i32 s21, s21, 32
	s_add_i32 s15, s15, 1
	v_add_u32_e32 v197, 1, v197
	s_cmp_lg_u32 s33, s21
	s_waitcnt lgkmcnt(0)
	v_mfma_f32_32x32x16_bf16 v[66:81], v[236:239], v[110:113], v[66:81]
	ds_read_b128 v[236:239], v190 offset:64
	s_waitcnt lgkmcnt(0)
	v_mfma_f32_32x32x16_bf16 v[66:81], v[236:239], v[106:109], v[66:81]
	ds_read_b128 v[236:239], v190 offset:96
	s_waitcnt lgkmcnt(0)
	v_mfma_f32_32x32x16_bf16 v[66:81], v[236:239], v[102:105], v[66:81]
	ds_read_b128 v[236:239], v190 offset:128
	s_waitcnt lgkmcnt(0)
	v_mfma_f32_32x32x16_bf16 v[66:81], v[236:239], v[98:101], v[66:81]
	ds_read_b128 v[236:239], v190 offset:160
	s_waitcnt lgkmcnt(0)
	v_mfma_f32_32x32x16_bf16 v[66:81], v[236:239], v[94:97], v[66:81]
	ds_read_b128 v[236:239], v190 offset:192
	s_waitcnt lgkmcnt(0)
	v_mfma_f32_32x32x16_bf16 v[66:81], v[236:239], v[90:93], v[66:81]
	ds_read_b128 v[236:239], v190 offset:224
	s_waitcnt lgkmcnt(0)
	v_mfma_f32_32x32x16_bf16 v[66:81], v[236:239], v[86:89], v[66:81]
	ds_read_b128 v[236:239], v190 offset:256
	s_waitcnt lgkmcnt(0)
	v_mfma_f32_32x32x16_bf16 v[66:81], v[236:239], v[122:125], v[66:81]
	ds_read_b128 v[236:239], v190 offset:288
	s_waitcnt lgkmcnt(0)
	v_mfma_f32_32x32x16_bf16 v[66:81], v[236:239], v[114:117], v[66:81]
	ds_read_b128 v[236:239], v190 offset:320
	s_waitcnt lgkmcnt(0)
	v_mfma_f32_32x32x16_bf16 v[66:81], v[236:239], v[126:129], v[66:81]
	ds_read_b128 v[236:239], v190 offset:352
	s_waitcnt lgkmcnt(0)
	v_mfma_f32_32x32x16_bf16 v[66:81], v[236:239], v[82:85], v[66:81]
	s_nop 11
	v_max_f32_e32 v184, v67, v67
	v_max_f32_e32 v185, v66, v66
	v_max_f32_e32 v184, v185, v184
	v_max3_f32 v184, v184, v68, v69
	v_max3_f32 v184, v184, v70, v71
	v_max3_f32 v184, v184, v72, v73
	v_max3_f32 v184, v184, v74, v75
	v_max3_f32 v184, v184, v76, v77
	v_max3_f32 v184, v184, v78, v79
	v_max3_f32 v184, v184, v80, v81
	v_mov_b32_e32 v185, v184
	s_nop 1
	v_permlane32_swap_b32 v185, v184
	s_waitcnt lgkmcnt(0)
	v_max3_f32 v185, v0, v184, v185
	v_mov_b32_e32 v184, v81
	v_pk_mul_f32 v[232:233], v[184:185], s[26:27] op_sel_hi:[1,0]
	v_sub_f32_e32 v0, v0, v185
	v_pk_fma_f32 v[66:67], v[66:67], s[26:27], v[232:233] op_sel:[0,0,1] op_sel_hi:[1,0,1] neg_lo:[0,0,1] neg_hi:[0,0,1]
	v_exp_f32_e32 v66, v66
	v_exp_f32_e32 v67, v67
	v_pk_fma_f32 v[68:69], v[68:69], s[26:27], v[232:233] op_sel:[0,0,1] op_sel_hi:[1,0,1] neg_lo:[0,0,1] neg_hi:[0,0,1]
	v_exp_f32_e32 v68, v68
	v_exp_f32_e32 v69, v69
	v_pk_fma_f32 v[70:71], v[70:71], s[26:27], v[232:233] op_sel:[0,0,1] op_sel_hi:[1,0,1] neg_lo:[0,0,1] neg_hi:[0,0,1]
	v_exp_f32_e32 v70, v70
	v_exp_f32_e32 v71, v71
	v_pk_fma_f32 v[72:73], v[72:73], s[26:27], v[232:233] op_sel:[0,0,1] op_sel_hi:[1,0,1] neg_lo:[0,0,1] neg_hi:[0,0,1]
	v_add_f32_e32 v184, v67, v66
	v_exp_f32_e32 v72, v72
	v_add_f32_e32 v184, v68, v184
	v_exp_f32_e32 v73, v73
	v_pk_fma_f32 v[74:75], v[74:75], s[26:27], v[232:233] op_sel:[0,0,1] op_sel_hi:[1,0,1] neg_lo:[0,0,1] neg_hi:[0,0,1]
	v_add_f32_e32 v184, v69, v184
	v_exp_f32_e32 v74, v74
	v_add_f32_e32 v184, v70, v184
	v_exp_f32_e32 v75, v75
	v_pk_fma_f32 v[76:77], v[76:77], s[26:27], v[232:233] op_sel:[0,0,1] op_sel_hi:[1,0,1] neg_lo:[0,0,1] neg_hi:[0,0,1]
	v_add_f32_e32 v184, v71, v184
	v_exp_f32_e32 v76, v76
	v_add_f32_e32 v184, v72, v184
	v_exp_f32_e32 v77, v77
	v_pk_fma_f32 v[78:79], v[78:79], s[26:27], v[232:233] op_sel:[0,0,1] op_sel_hi:[1,0,1] neg_lo:[0,0,1] neg_hi:[0,0,1]
	v_add_f32_e32 v184, v73, v184
	v_exp_f32_e32 v78, v78
	v_add_f32_e32 v184, v74, v184
	v_exp_f32_e32 v79, v79
	v_fma_f32 v80, v80, s26, -v233
	v_add_f32_e32 v184, v75, v184
	v_exp_f32_e32 v80, v80
	v_sub_f32_e32 v81, v232, v233
	v_add_f32_e32 v184, v76, v184
	v_exp_f32_e32 v81, v81
	v_add_f32_e32 v184, v77, v184
	v_add_f32_e32 v184, v78, v184
	v_mul_f32_e32 v0, 0x3dd53b94, v0
	v_add_f32_e32 v184, v79, v184
	v_exp_f32_e32 v0, v0
	v_add_f32_e32 v184, v80, v184
	v_add_f32_e32 v184, v81, v184
	v_cvt_pk_bf16_f32 v66, v66, v67
	v_cvt_pk_bf16_f32 v67, v68, v69
	v_cvt_pk_bf16_f32 v68, v70, v71
	v_cvt_pk_bf16_f32 v69, v72, v73
	v_cvt_pk_bf16_f32 v70, v74, v75
	v_cvt_pk_bf16_f32 v71, v76, v77
	v_cvt_pk_bf16_f32 v72, v78, v79
	v_cvt_pk_bf16_f32 v73, v80, v81
	ds_read2_b64 v[74:77], v234 offset1:2
	ds_read2_b64 v[78:81], v234 offset0:4 offset1:6
	v_pk_mul_f32 v[16:17], v[16:17], v[0:1] op_sel_hi:[1,0]
	v_pk_mul_f32 v[14:15], v[14:15], v[0:1] op_sel_hi:[1,0]
	v_pk_mul_f32 v[12:13], v[12:13], v[0:1] op_sel_hi:[1,0]
	v_pk_mul_f32 v[10:11], v[10:11], v[0:1] op_sel_hi:[1,0]
	v_pk_mul_f32 v[8:9], v[8:9], v[0:1] op_sel_hi:[1,0]
	v_pk_mul_f32 v[6:7], v[6:7], v[0:1] op_sel_hi:[1,0]
	v_pk_mul_f32 v[4:5], v[4:5], v[0:1] op_sel_hi:[1,0]
	v_pk_mul_f32 v[2:3], v[2:3], v[0:1] op_sel_hi:[1,0]
	v_add_u32_e32 v233, 0xd000, v227
	v_pk_mul_f32 v[48:49], v[48:49], v[0:1] op_sel_hi:[1,0]
	s_waitcnt lgkmcnt(1)
	v_mfma_f32_32x32x16_bf16 v[2:17], v[74:77], v[66:69], v[2:17]
	ds_read2_b64 v[74:77], v233 offset0:32 offset1:34
	v_mul_f32_e64 v46, v46, v0
	v_mul_f32_e64 v47, v47, v0
	v_mul_f32_e64 v44, v44, v0
	v_mul_f32_e64 v45, v45, v0
	v_pk_mul_f32 v[42:43], v[42:43], v[0:1] op_sel_hi:[1,0]
	v_pk_mul_f32 v[40:41], v[40:41], v[0:1] op_sel_hi:[1,0]
	v_pk_mul_f32 v[38:39], v[38:39], v[0:1] op_sel_hi:[1,0]
	v_pk_mul_f32 v[36:37], v[36:37], v[0:1] op_sel_hi:[1,0]
	v_pk_mul_f32 v[34:35], v[34:35], v[0:1] op_sel_hi:[1,0]
	v_pk_mul_f32 v[64:65], v[64:65], v[0:1] op_sel_hi:[1,0]
	v_pk_mul_f32 v[62:63], v[62:63], v[0:1] op_sel_hi:[1,0]
	s_waitcnt lgkmcnt(0)
	v_mfma_f32_32x32x16_bf16 v[34:49], v[74:77], v[66:69], v[34:49]
	ds_read2_b64 v[74:77], v233 offset0:36 offset1:38
	v_mul_f32_e64 v60, v60, v0
	v_mul_f32_e64 v61, v61, v0
	v_mul_f32_e64 v58, v58, v0
	v_mul_f32_e64 v59, v59, v0
	v_pk_mul_f32 v[56:57], v[56:57], v[0:1] op_sel_hi:[1,0]
	v_pk_mul_f32 v[54:55], v[54:55], v[0:1] op_sel_hi:[1,0]
	v_pk_mul_f32 v[52:53], v[52:53], v[0:1] op_sel_hi:[1,0]
	v_pk_mul_f32 v[50:51], v[50:51], v[0:1] op_sel_hi:[1,0]
	s_waitcnt lgkmcnt(0)
	v_mfma_f32_32x32x16_bf16 v[34:49], v[74:77], v[70:73], v[34:49]
	ds_read2_b64 v[74:77], v231 offset0:64 offset1:66
	v_add_u32_e32 v232, 0xe000, v227
	v_mul_f32_e64 v32, v32, v0
	v_mul_f32_e64 v33, v33, v0
	v_mul_f32_e64 v30, v30, v0
	v_mul_f32_e64 v31, v31, v0
	v_pk_mul_f32 v[28:29], v[28:29], v[0:1] op_sel_hi:[1,0]
	v_pk_mul_f32 v[26:27], v[26:27], v[0:1] op_sel_hi:[1,0]
	v_pk_mul_f32 v[24:25], v[24:25], v[0:1] op_sel_hi:[1,0]
	s_waitcnt lgkmcnt(0)
	v_mfma_f32_32x32x16_bf16 v[50:65], v[74:77], v[66:69], v[50:65]
	ds_read2_b64 v[74:77], v231 offset0:68 offset1:70
	v_mul_f32_e64 v22, v22, v0
	v_mul_f32_e64 v23, v23, v0
	v_mul_f32_e64 v20, v20, v0
	v_mul_f32_e64 v21, v21, v0
	v_pk_mul_f32 v[18:19], v[18:19], v[0:1] op_sel_hi:[1,0]
	v_fmac_f32_e32 v184, v235, v0
	s_waitcnt lgkmcnt(0)
	v_mfma_f32_32x32x16_bf16 v[50:65], v[74:77], v[70:73], v[50:65]
	ds_read2_b64 v[74:77], v232 offset0:96 offset1:98
	s_waitcnt lgkmcnt(0)
	v_mfma_f32_32x32x16_bf16 v[18:33], v[74:77], v[66:69], v[18:33]
	ds_read2_b64 v[66:69], v232 offset0:100 offset1:102
	s_waitcnt lgkmcnt(0)
	s_barrier
	v_mfma_f32_32x32x16_bf16 v[2:17], v[78:81], v[70:73], v[2:17]
	v_mfma_f32_32x32x16_bf16 v[18:33], v[66:69], v[70:73], v[18:33]
	s_cbranch_scc1 .LBB0_522
	s_waitcnt vmcnt(9)
	ds_write_b128 v191, v[130:133]
	s_waitcnt vmcnt(8)
	ds_write2_b64 v192, v[134:135], v[136:137] offset1:1
	s_waitcnt vmcnt(7)
	ds_write_b128 v191, v[142:145] offset:12800
	s_waitcnt vmcnt(6)
	ds_write2_b64 v228, v[138:139], v[140:141] offset1:1
	s_waitcnt vmcnt(5)
	ds_write_b128 v191, v[150:153] offset:25600
	s_waitcnt vmcnt(4)
	ds_write2_b64 v229, v[146:147], v[148:149] offset1:1
	s_waitcnt vmcnt(3)
	ds_write_b128 v191, v[158:161] offset:38400
	s_waitcnt vmcnt(2)
	ds_write2_b64 v230, v[154:155], v[156:157] offset1:1
	s_waitcnt vmcnt(1)
	ds_write_b128 v194, v[162:165] offset:256
	s_waitcnt vmcnt(0)
	ds_write_b128 v195, v[166:169] offset:256
	s_waitcnt lgkmcnt(0)
	s_barrier
	ds_read_b128 v[66:69], v190
	ds_read_b128 v[130:133], v190 offset:32
	s_waitcnt lgkmcnt(1)
	v_mfma_f32_32x32x16_bf16 v[66:81], v[66:69], v[118:121], 0
	v_readlane_b32 s4, v253, 17
	s_mov_b32 s7, 0xf149f2ca
	s_mov_b32 s39, s31
	s_waitcnt lgkmcnt(0)
	v_mfma_f32_32x32x16_bf16 v[66:81], v[130:133], v[110:113], v[66:81]
	ds_read_b128 v[110:113], v190 offset:64
	ds_read_b128 v[118:121], v190 offset:96
	s_waitcnt lgkmcnt(1)
	v_mfma_f32_32x32x16_bf16 v[66:81], v[110:113], v[106:109], v[66:81]
	v_ashrrev_i32_e32 v110, 6, v188
	s_waitcnt lgkmcnt(0)
	v_mfma_f32_32x32x16_bf16 v[66:81], v[118:121], v[102:105], v[66:81]
	ds_read_b128 v[102:105], v190 offset:128
	ds_read_b128 v[106:109], v190 offset:160
	s_waitcnt lgkmcnt(1)
	v_mfma_f32_32x32x16_bf16 v[66:81], v[102:105], v[98:101], v[66:81]
	s_waitcnt lgkmcnt(0)
	v_mfma_f32_32x32x16_bf16 v[66:81], v[106:109], v[94:97], v[66:81]
	ds_read_b128 v[94:97], v190 offset:192
	ds_read_b128 v[98:101], v190 offset:224
	s_waitcnt lgkmcnt(1)
	v_mfma_f32_32x32x16_bf16 v[66:81], v[94:97], v[90:93], v[66:81]
	s_waitcnt lgkmcnt(0)
	v_mfma_f32_32x32x16_bf16 v[66:81], v[98:101], v[86:89], v[66:81]
	ds_read_b128 v[86:89], v190 offset:256
	ds_read_b128 v[90:93], v190 offset:288
	s_waitcnt lgkmcnt(1)
	v_mfma_f32_32x32x16_bf16 v[66:81], v[86:89], v[122:125], v[66:81]
	s_waitcnt lgkmcnt(0)
	v_mfma_f32_32x32x16_bf16 v[66:81], v[90:93], v[114:117], v[66:81]
	ds_read_b128 v[90:93], v190 offset:320
	ds_read_b128 v[86:89], v190 offset:352
	s_waitcnt lgkmcnt(1)
	v_mfma_f32_32x32x16_bf16 v[66:81], v[90:93], v[126:129], v[66:81]
	ds_read2_b64 v[90:93], v234 offset1:2
	ds_read2_b64 v[94:97], v234 offset0:4 offset1:6
	ds_read2_b64 v[98:101], v233 offset0:32 offset1:34
	s_waitcnt lgkmcnt(3)
	v_mfma_f32_32x32x16_bf16 v[66:81], v[86:89], v[82:85], v[66:81]
	ds_read2_b64 v[84:87], v233 offset0:36 offset1:38
	ds_read2_b64 v[102:105], v231 offset0:64 offset1:66
	s_nop 9
	v_max_f32_e32 v0, v67, v67
	v_max_f32_e32 v82, v66, v66
	v_max_f32_e32 v0, v82, v0
	v_max3_f32 v0, v0, v68, v69
	v_max3_f32 v0, v0, v70, v71
	v_max3_f32 v0, v0, v72, v73
	v_max3_f32 v0, v0, v74, v75
	v_max3_f32 v0, v0, v76, v77
	v_max3_f32 v0, v0, v78, v79
	v_max3_f32 v0, v0, v80, v81
	v_mov_b32_e32 v83, v0
	v_mov_b32_e32 v88, v81
	v_and_b32_e32 v82, 1, v110
	v_permlane32_swap_b32 v83, v0
	s_waitcnt lgkmcnt(0)
	v_max3_f32 v89, v185, v0, v83
	v_sub_f32_e32 v0, v185, v89
	v_pk_mul_f32 v[106:107], v[88:89], s[26:27] op_sel_hi:[1,0]
	v_mul_f32_e32 v0, 0x3dd53b94, v0
	v_fma_f32 v66, v66, s26, -v107
	v_fma_f32 v67, v67, s26, -v107
	v_fma_f32 v68, v68, s26, -v107
	v_fma_f32 v69, v69, s26, -v107
	v_fma_f32 v70, v70, s26, -v107
	v_fma_f32 v71, v71, s26, -v107
	v_fma_f32 v72, v72, s26, -v107
	v_fma_f32 v73, v73, s26, -v107
	v_exp_f32_e32 v0, v0
	v_exp_f32_e32 v88, v66
	v_exp_f32_e32 v111, v67
	v_exp_f32_e32 v112, v68
	v_exp_f32_e32 v113, v69
	v_exp_f32_e32 v114, v70
	v_exp_f32_e32 v115, v71
	v_exp_f32_e32 v116, v72
	v_exp_f32_e32 v117, v73
	v_fma_f32 v74, v74, s26, -v107
	v_fma_f32 v75, v75, s26, -v107
	v_fma_f32 v76, v76, s26, -v107
	v_fma_f32 v77, v77, s26, -v107
	v_fma_f32 v78, v78, s26, -v107
	v_fma_f32 v79, v79, s26, -v107
	v_fma_f32 v80, v80, s26, -v107
	v_sub_f32_e32 v83, v106, v107
	v_exp_f32_e32 v118, v74
	v_exp_f32_e32 v119, v75
	v_exp_f32_e32 v120, v76
	v_exp_f32_e32 v121, v77
	v_exp_f32_e32 v122, v78
	v_exp_f32_e32 v123, v79
	v_exp_f32_e32 v124, v80
	v_pk_mul_f32 v[80:81], v[16:17], v[0:1] op_sel_hi:[1,0]
	v_pk_mul_f32 v[78:79], v[14:15], v[0:1] op_sel_hi:[1,0]
	v_pk_mul_f32 v[76:77], v[12:13], v[0:1] op_sel_hi:[1,0]
	v_pk_mul_f32 v[74:75], v[10:11], v[0:1] op_sel_hi:[1,0]
	v_pk_mul_f32 v[72:73], v[8:9], v[0:1] op_sel_hi:[1,0]
	v_pk_mul_f32 v[70:71], v[6:7], v[0:1] op_sel_hi:[1,0]
	v_pk_mul_f32 v[68:69], v[4:5], v[0:1] op_sel_hi:[1,0]
	v_pk_mul_f32 v[66:67], v[2:3], v[0:1] op_sel_hi:[1,0]
	v_pk_mul_f32 v[16:17], v[48:49], v[0:1] op_sel_hi:[1,0]
	v_cvt_pk_bf16_f32 v106, v88, v111
	v_cvt_pk_bf16_f32 v107, v112, v113
	v_cvt_pk_bf16_f32 v108, v114, v115
	v_cvt_pk_bf16_f32 v109, v116, v117
	v_pk_mul_f32 v[14:15], v[46:47], v[0:1] op_sel_hi:[1,0]
	v_pk_mul_f32 v[12:13], v[44:45], v[0:1] op_sel_hi:[1,0]
	v_pk_mul_f32 v[10:11], v[42:43], v[0:1] op_sel_hi:[1,0]
	v_pk_mul_f32 v[8:9], v[40:41], v[0:1] op_sel_hi:[1,0]
	v_pk_mul_f32 v[6:7], v[38:39], v[0:1] op_sel_hi:[1,0]
	v_pk_mul_f32 v[4:5], v[36:37], v[0:1] op_sel_hi:[1,0]
	v_pk_mul_f32 v[2:3], v[34:35], v[0:1] op_sel_hi:[1,0]
	v_pk_mul_f32 v[48:49], v[64:65], v[0:1] op_sel_hi:[1,0]
	v_pk_mul_f32 v[46:47], v[62:63], v[0:1] op_sel_hi:[1,0]
	v_pk_mul_f32 v[44:45], v[60:61], v[0:1] op_sel_hi:[1,0]
	v_pk_mul_f32 v[42:43], v[58:59], v[0:1] op_sel_hi:[1,0]
	v_pk_mul_f32 v[40:41], v[56:57], v[0:1] op_sel_hi:[1,0]
	v_pk_mul_f32 v[38:39], v[54:55], v[0:1] op_sel_hi:[1,0]
	v_pk_mul_f32 v[36:37], v[52:53], v[0:1] op_sel_hi:[1,0]
	v_pk_mul_f32 v[34:35], v[50:51], v[0:1] op_sel_hi:[1,0]
	ds_read2_b64 v[50:53], v231 offset0:68 offset1:70
	v_add_f32_e32 v54, 0, v88
	v_mfma_f32_32x32x16_bf16 v[34:49], v[102:105], v[106:109], v[34:49]
	v_add_f32_e32 v54, v111, v54
	v_exp_f32_e32 v83, v83
	v_add_f32_e32 v54, v112, v54
	v_add_f32_e32 v54, v113, v54
	v_add_f32_e32 v58, v114, v54
	ds_read2_b64 v[54:57], v232 offset0:96 offset1:98
	v_cvt_pk_bf16_f32 v62, v118, v119
	v_cvt_pk_bf16_f32 v63, v120, v121
	v_cvt_pk_bf16_f32 v64, v122, v123
	v_cvt_pk_bf16_f32 v65, v124, v83
	v_mfma_f32_32x32x16_bf16 v[66:81], v[90:93], v[106:109], v[66:81]
	v_mul_f32_e64 v32, v32, v0
	v_mul_f32_e64 v33, v33, v0
	v_mul_f32_e64 v30, v30, v0
	v_mul_f32_e64 v31, v31, v0
	v_mul_f32_e64 v28, v28, v0
	v_mul_f32_e64 v29, v29, v0
	v_pk_mul_f32 v[26:27], v[26:27], v[0:1] op_sel_hi:[1,0]
	v_pk_mul_f32 v[24:25], v[24:25], v[0:1] op_sel_hi:[1,0]
	v_pk_mul_f32 v[22:23], v[22:23], v[0:1] op_sel_hi:[1,0]
	v_pk_mul_f32 v[20:21], v[20:21], v[0:1] op_sel_hi:[1,0]
	s_waitcnt lgkmcnt(1)
	v_mfma_f32_32x32x16_bf16 v[34:49], v[50:53], v[62:65], v[34:49]
	v_add_f32_e32 v50, v115, v58
	v_add_f32_e32 v50, v116, v50
	v_add_f32_e32 v50, v117, v50
	v_add_f32_e32 v50, v118, v50
	v_add_f32_e32 v50, v119, v50
	v_pk_mul_f32 v[18:19], v[18:19], v[0:1] op_sel_hi:[1,0]
	v_add_f32_e32 v58, v120, v50
	ds_read2_b64 v[50:53], v232 offset0:100 offset1:102
	s_waitcnt lgkmcnt(1)
	v_mfma_f32_32x32x16_bf16 v[18:33], v[54:57], v[106:109], v[18:33]
	v_add_f32_e32 v54, v121, v58
	v_add_f32_e32 v54, v122, v54
	v_add_f32_e32 v54, v123, v54
	v_add_f32_e32 v54, v124, v54
	v_add_f32_e32 v54, v83, v54
	v_fmac_f32_e32 v54, v184, v0
	v_mov_b32_e32 v0, v54
	v_mfma_f32_32x32x16_bf16 v[2:17], v[98:101], v[106:109], v[2:17]
	s_nop 1
	v_permlane32_swap_b32 v0, v54
	s_waitcnt lgkmcnt(0)
	s_barrier
	v_add_f32_e32 v0, v54, v0
	v_mfma_f32_32x32x16_bf16 v[66:81], v[94:97], v[62:65], v[66:81]
	v_mfma_f32_32x32x16_bf16 v[18:33], v[50:53], v[62:65], v[18:33]
	v_lshlrev_b32_e32 v50, 9, v110
	v_lshlrev_b32_e32 v51, 2, v186
	v_add3_u32 v50, s4, v50, v51
	ds_write2st64_b32 v50, v89, v0 offset1:1
	v_lshlrev_b32_e32 v0, 14, v110
	v_add3_u32 v0, 0, v0, v51
	v_mfma_f32_32x32x16_bf16 v[2:17], v[84:87], v[62:65], v[2:17]
	s_nop 3
	ds_write2st64_b32 v0, v66, v67 offset1:1
	ds_write2st64_b32 v0, v68, v69 offset0:2 offset1:3
	ds_write2st64_b32 v0, v70, v71 offset0:4 offset1:5
	ds_write2st64_b32 v0, v72, v73 offset0:6 offset1:7
	ds_write2st64_b32 v0, v74, v75 offset0:8 offset1:9
	ds_write2st64_b32 v0, v76, v77 offset0:10 offset1:11
	ds_write2st64_b32 v0, v78, v79 offset0:12 offset1:13
	ds_write2st64_b32 v0, v80, v81 offset0:14 offset1:15
	ds_write2st64_b32 v0, v2, v3 offset0:16 offset1:17
	ds_write2st64_b32 v0, v4, v5 offset0:18 offset1:19
	ds_write2st64_b32 v0, v6, v7 offset0:20 offset1:21
	ds_write2st64_b32 v0, v8, v9 offset0:22 offset1:23
	ds_write2st64_b32 v0, v10, v11 offset0:24 offset1:25
	ds_write2st64_b32 v0, v12, v13 offset0:26 offset1:27
	ds_write2st64_b32 v0, v14, v15 offset0:28 offset1:29
	ds_write2st64_b32 v0, v16, v17 offset0:30 offset1:31
	ds_write2st64_b32 v0, v34, v35 offset0:32 offset1:33
	ds_write2st64_b32 v0, v36, v37 offset0:34 offset1:35
	ds_write2st64_b32 v0, v38, v39 offset0:36 offset1:37
	ds_write2st64_b32 v0, v40, v41 offset0:38 offset1:39
	ds_write2st64_b32 v0, v42, v43 offset0:40 offset1:41
	ds_write2st64_b32 v0, v44, v45 offset0:42 offset1:43
	ds_write2st64_b32 v0, v46, v47 offset0:44 offset1:45
	ds_write2st64_b32 v0, v48, v49 offset0:46 offset1:47
	ds_write2st64_b32 v0, v18, v19 offset0:48 offset1:49
	ds_write2st64_b32 v0, v20, v21 offset0:50 offset1:51
	ds_write2st64_b32 v0, v22, v23 offset0:52 offset1:53
	ds_write2st64_b32 v0, v24, v25 offset0:54 offset1:55
	ds_write2st64_b32 v0, v26, v27 offset0:56 offset1:57
	ds_write2st64_b32 v0, v28, v29 offset0:58 offset1:59
	ds_write2st64_b32 v0, v30, v31 offset0:60 offset1:61
	ds_write2st64_b32 v0, v32, v33 offset0:62 offset1:63
	v_lshlrev_b32_e32 v0, 9, v82
	v_add3_u32 v0, s4, v0, v51
	s_waitcnt lgkmcnt(0)
	s_barrier
	ds_read2st64_b32 v[4:5], v0 offset1:1
	ds_read2st64_b32 v[6:7], v0 offset0:4 offset1:5
	ds_read2st64_b32 v[8:9], v0 offset0:8 offset1:9
	ds_read2st64_b32 v[10:11], v0 offset0:12 offset1:13
	s_lshl_b64 s[4:5], s[38:39], 11
	s_waitcnt lgkmcnt(2)
	v_max3_f32 v0, v4, s7, v6
	s_add_u32 s7, s80, s4
	s_waitcnt lgkmcnt(0)
	v_max3_f32 v0, v0, v8, v10
	v_sub_f32_e32 v2, v4, v0
	v_mul_f32_e32 v2, 0x3dd53b94, v2
	v_exp_f32_e32 v3, v2
	v_sub_f32_e32 v2, v6, v0
	v_mul_f32_e32 v2, 0x3dd53b94, v2
	v_exp_f32_e32 v2, v2
	v_mov_b32_e32 v4, v7
	s_addc_u32 s10, s81, s5
	v_pk_mul_f32 v[6:7], v[4:5], v[2:3]
	v_sub_f32_e32 v4, v8, v0
	v_sub_f32_e32 v0, v10, v0
	v_mul_f32_e32 v4, 0x3dd53b94, v4
	v_mul_f32_e32 v0, 0x3dd53b94, v0
	v_exp_f32_e32 v5, v4
	v_exp_f32_e32 v4, v0
	v_add_f32_e32 v0, 0, v7
	v_mov_b32_e32 v8, v11
	v_add_f32_e32 v0, v6, v0
	v_pk_mul_f32 v[6:7], v[8:9], v[4:5]
	s_nop 0
	v_add_f32_e32 v0, v7, v0
	v_add_f32_e32 v0, v6, v0
	v_div_scale_f32 v6, s[4:5], v0, v0, 1.0
	v_rcp_f32_e32 v7, v6
	s_lshl_b32 s4, s14, 1
	s_add_u32 s38, s7, s4
	s_addc_u32 s39, s10, 0
	v_fma_f32 v8, -v6, v7, 1.0
	v_fmac_f32_e32 v7, v8, v7
	v_div_scale_f32 v8, vcc, 1.0, v0, 1.0
	v_mul_f32_e32 v9, v8, v7
	v_fma_f32 v10, -v6, v9, v8
	v_fmac_f32_e32 v9, v10, v7
	v_fma_f32 v6, -v6, v9, v8
	v_div_fmas_f32 v6, v6, v7, v9
	v_div_fixup_f32 v0, v6, v0, 1.0
	v_lshl_add_u32 v6, v82, 14, 0
	v_lshlrev_b32_e32 v7, 12, v177
	v_add3_u32 v7, v6, v7, v51
	ds_read2st64_b32 v[8:9], v7 offset1:1
	ds_read2st64_b32 v[10:11], v7 offset0:128 offset1:129
	v_mov_b32_e32 v6, v3
	v_add_u32_e32 v24, 0x10000, v7
	v_add_u32_e32 v25, 0x18000, v7
	v_add_u32_e32 v27, 0x10100, v7
	v_add_u32_e32 v28, 0x18100, v7
	ds_read2st64_b32 v[12:13], v7 offset0:2 offset1:3
	ds_read2st64_b32 v[14:15], v7 offset0:4 offset1:5
	ds_read2st64_b32 v[16:17], v7 offset0:6 offset1:7
	s_waitcnt lgkmcnt(4)
	v_pk_fma_f32 v[8:9], v[8:9], v[6:7], 0 op_sel_hi:[1,0,0]
	v_add_u32_e32 v31, 0x18300, v7
	ds_read2st64_b32 v[18:19], v7 offset0:130 offset1:131
	ds_read2st64_b32 v[20:21], v7 offset0:132 offset1:133
	ds_read2st64_b32 v[22:23], v7 offset0:134 offset1:135
	s_waitcnt lgkmcnt(6)
	v_pk_fma_f32 v[8:9], v[10:11], v[2:3], v[8:9] op_sel_hi:[1,0,1]
	v_mov_b32_e32 v10, v5
	v_add_u32_e32 v3, 0x10200, v7
	v_add_u32_e32 v5, 0x18200, v7
	v_add_u32_e32 v11, 0x10300, v7
	ds_read_b32 v24, v24
	ds_read_b32 v26, v25
	ds_read_b32 v25, v27
	ds_read_b32 v27, v28
	ds_read_b32 v28, v3
	ds_read_b32 v30, v5
	ds_read_b32 v29, v11
	ds_read_b32 v31, v31
	s_waitcnt lgkmcnt(13)
	v_pk_fma_f32 v[12:13], v[6:7], v[12:13], 0 op_sel_hi:[0,1,0]
	s_waitcnt lgkmcnt(5)
	v_pk_fma_f32 v[8:9], v[10:11], v[24:25], v[8:9] op_sel_hi:[0,1,1]
	v_pk_fma_f32 v[12:13], v[2:3], v[18:19], v[12:13] op_sel_hi:[0,1,1]
	v_add_u32_e32 v3, 0x10400, v7
	v_pk_fma_f32 v[14:15], v[6:7], v[14:15], 0 op_sel_hi:[0,1,0]
	s_waitcnt lgkmcnt(4)
	v_pk_fma_f32 v[8:9], v[4:5], v[26:27], v[8:9] op_sel_hi:[0,1,1]
	s_waitcnt lgkmcnt(1)
	v_pk_fma_f32 v[12:13], v[10:11], v[28:29], v[12:13] op_sel_hi:[0,1,1]
	v_add_u32_e32 v11, 0x10500, v7
	v_add_u32_e32 v24, 0x18500, v7
	v_pk_fma_f32 v[14:15], v[2:3], v[20:21], v[14:15] op_sel_hi:[0,1,1]
	v_add_u32_e32 v25, 0x10600, v7
	v_add_u32_e32 v26, 0x18600, v7
	v_add_u32_e32 v27, 0x10700, v7
	s_waitcnt lgkmcnt(0)
	v_pk_fma_f32 v[12:13], v[4:5], v[30:31], v[12:13] op_sel_hi:[0,1,1]
	v_add_u32_e32 v5, 0x18400, v7
	v_add_u32_e32 v28, 0x18700, v7
	ds_read_b32 v18, v3
	ds_read_b32 v20, v5
	ds_read_b32 v19, v11
	ds_read_b32 v21, v24
	ds_read_b32 v24, v25
	ds_read_b32 v26, v26
	ds_read_b32 v25, v27
	ds_read_b32 v27, v28
	s_waitcnt lgkmcnt(5)
	v_pk_fma_f32 v[14:15], v[10:11], v[18:19], v[14:15] op_sel_hi:[0,1,1]
	s_waitcnt lgkmcnt(4)
	v_pk_fma_f32 v[14:15], v[4:5], v[20:21], v[14:15] op_sel_hi:[0,1,1]
	ds_read2st64_b32 v[18:19], v7 offset0:8 offset1:9
	ds_read2st64_b32 v[20:21], v7 offset0:136 offset1:137
	v_pk_fma_f32 v[16:17], v[6:7], v[16:17], 0 op_sel_hi:[0,1,0]
	v_pk_fma_f32 v[16:17], v[2:3], v[22:23], v[16:17] op_sel_hi:[0,1,1]
	s_waitcnt lgkmcnt(3)
	v_pk_fma_f32 v[16:17], v[10:11], v[24:25], v[16:17] op_sel_hi:[0,1,1]
	s_waitcnt lgkmcnt(2)
	v_pk_fma_f32 v[16:17], v[4:5], v[26:27], v[16:17] op_sel_hi:[0,1,1]
	v_add_u32_e32 v3, 0x10800, v7
	v_add_u32_e32 v35, 0x18900, v7
	ds_read2st64_b32 v[22:23], v7 offset0:10 offset1:11
	ds_read2st64_b32 v[24:25], v7 offset0:12 offset1:13
	ds_read2st64_b32 v[26:27], v7 offset0:14 offset1:15
	s_waitcnt lgkmcnt(4)
	v_pk_fma_f32 v[18:19], v[6:7], v[18:19], 0 op_sel_hi:[0,1,0]
	v_add_u32_e32 v36, 0x10a00, v7
	v_add_u32_e32 v37, 0x18a00, v7
	v_add_u32_e32 v39, 0x10b00, v7
	v_add_u32_e32 v5, 0x18800, v7
	v_add_u32_e32 v11, 0x10900, v7
	ds_read2st64_b32 v[28:29], v7 offset0:138 offset1:139
	ds_read2st64_b32 v[30:31], v7 offset0:140 offset1:141
	ds_read2st64_b32 v[32:33], v7 offset0:142 offset1:143
	s_waitcnt lgkmcnt(6)
	v_pk_fma_f32 v[18:19], v[2:3], v[20:21], v[18:19] op_sel_hi:[0,1,1]
	v_add_u32_e32 v40, 0x18b00, v7
	ds_read_b32 v20, v3
	ds_read_b32 v34, v5
	ds_read_b32 v21, v11
	ds_read_b32 v35, v35
	ds_read_b32 v36, v36
	ds_read_b32 v38, v37
	ds_read_b32 v37, v39
	ds_read_b32 v39, v40
	s_waitcnt lgkmcnt(5)
	v_pk_fma_f32 v[18:19], v[10:11], v[20:21], v[18:19] op_sel_hi:[0,1,1]
	v_pk_fma_f32 v[20:21], v[6:7], v[22:23], 0 op_sel_hi:[0,1,0]
	v_pk_fma_f32 v[20:21], v[2:3], v[28:29], v[20:21] op_sel_hi:[0,1,1]
	v_add_u32_e32 v3, 0x10c00, v7
	v_pk_fma_f32 v[22:23], v[6:7], v[24:25], 0 op_sel_hi:[0,1,0]
	s_waitcnt lgkmcnt(4)
	v_pk_fma_f32 v[18:19], v[4:5], v[34:35], v[18:19] op_sel_hi:[0,1,1]
	s_waitcnt lgkmcnt(1)
	v_pk_fma_f32 v[20:21], v[10:11], v[36:37], v[20:21] op_sel_hi:[0,1,1]
	v_add_u32_e32 v29, 0x18d00, v7
	v_pk_fma_f32 v[22:23], v[2:3], v[30:31], v[22:23] op_sel_hi:[0,1,1]
	v_add_u32_e32 v30, 0x10e00, v7
	v_add_u32_e32 v31, 0x18e00, v7
	v_add_u32_e32 v35, 0x10f00, v7
	s_waitcnt lgkmcnt(0)
	v_pk_fma_f32 v[20:21], v[4:5], v[38:39], v[20:21] op_sel_hi:[0,1,1]
	v_add_u32_e32 v5, 0x18c00, v7
	v_add_u32_e32 v11, 0x10d00, v7
	v_add_u32_e32 v7, 0x18f00, v7
	ds_read_b32 v24, v3
	ds_read_b32 v28, v5
	ds_read_b32 v25, v11
	ds_read_b32 v29, v29
	ds_read_b32 v30, v30
	ds_read_b32 v34, v31
	ds_read_b32 v31, v35
	ds_read_b32 v35, v7
	v_pk_fma_f32 v[6:7], v[6:7], v[26:27], 0 op_sel_hi:[0,1,0]
	v_pk_fma_f32 v[2:3], v[2:3], v[32:33], v[6:7] op_sel_hi:[0,1,1]
	s_waitcnt lgkmcnt(5)
	v_pk_fma_f32 v[22:23], v[10:11], v[24:25], v[22:23] op_sel_hi:[0,1,1]
	s_waitcnt lgkmcnt(1)
	v_pk_fma_f32 v[2:3], v[10:11], v[30:31], v[2:3] op_sel_hi:[0,1,1]
	v_pk_fma_f32 v[22:23], v[4:5], v[28:29], v[22:23] op_sel_hi:[0,1,1]
	s_waitcnt lgkmcnt(0)
	v_pk_fma_f32 v[2:3], v[4:5], v[34:35], v[2:3] op_sel_hi:[0,1,1]
	v_pk_mul_f32 v[8:9], v[8:9], v[0:1] op_sel_hi:[1,0]
	v_pk_mul_f32 v[12:13], v[0:1], v[12:13] op_sel_hi:[0,1]
	v_pk_mul_f32 v[14:15], v[0:1], v[14:15] op_sel_hi:[0,1]
	v_pk_mul_f32 v[16:17], v[0:1], v[16:17] op_sel_hi:[0,1]
	v_pk_mul_f32 v[18:19], v[0:1], v[18:19] op_sel_hi:[0,1]
	v_pk_mul_f32 v[20:21], v[0:1], v[20:21] op_sel_hi:[0,1]
	v_pk_mul_f32 v[22:23], v[0:1], v[22:23] op_sel_hi:[0,1]
	v_pk_mul_f32 v[2:3], v[0:1], v[2:3] op_sel_hi:[0,1]
	v_lshlrev_b32_e32 v0, 11, v175
	v_lshl_or_b32 v0, v82, 16, v0
	v_lshlrev_b32_e32 v6, 5, v177
	v_lshl_add_u64 v[4:5], s[38:39], 0, v[0:1]
	v_ashrrev_i32_e32 v7, 31, v6
	v_lshl_add_u64 v[4:5], v[6:7], 1, v[4:5]
	v_mov_b32_e32 v177, v1
	v_lshl_add_u64 v[4:5], v[4:5], 0, v[176:177]
	s_mov_b64 s[4:5], 0x4328400
	v_lshl_add_u64 v[6:7], v[4:5], 0, s[4:5]
	s_mov_b32 s4, 0x4328000
	v_add_co_u32_e32 v4, vcc, s4, v4
	v_cvt_pk_bf16_f32 v8, v8, v9
	v_cvt_pk_bf16_f32 v9, v12, v13
	v_addc_co_u32_e32 v5, vcc, 0, v5, vcc
	global_store_dwordx2 v[4:5], v[8:9], off offset:1024
	v_cvt_pk_bf16_f32 v4, v14, v15
	v_cvt_pk_bf16_f32 v5, v16, v17
	global_store_dwordx2 v[6:7], v[4:5], off offset:16
	v_cvt_pk_bf16_f32 v4, v18, v19
	v_cvt_pk_bf16_f32 v5, v20, v21
	global_store_dwordx2 v[6:7], v[4:5], off offset:32
	v_cvt_pk_bf16_f32 v4, v22, v23
	v_cvt_pk_bf16_f32 v5, v2, v3
	global_store_dwordx2 v[6:7], v[4:5], off offset:48
	s_barrier
	s_mov_b64 s[14:15], 0

.LBB0_592:
	s_cmp_lt_u32 s14, s7
	s_cselect_b32 s4, 0, s7
	s_cselect_b32 s5, s24, s1
	s_lshl_b32 s4, s4, 5
	s_sub_i32 s4, s5, s4
	s_add_i32 s30, s15, s4
	s_add_i32 s4, s10, s14
	v_add_u32_e32 v66, s30, v158
	s_cmp_lt_u32 s4, s7
	v_ashrrev_i32_e32 v67, 31, v66
	s_cselect_b32 s4, 0, s7
	v_lshlrev_b64 v[66:67], 9, v[66:67]
	s_cselect_b32 s5, s24, s1
	s_lshl_b32 s4, s4, 5
	v_add_u32_e32 v166, 0x8800, v161
	v_add_u32_e32 v167, 0xac00, v161
	v_add_u32_e32 v168, 0xd000, v161
	v_add_u32_e32 v169, 0xf400, v161
	v_lshl_add_u64 v[66:67], v[150:151], 0, v[66:67]
	s_sub_i32 s4, s5, s4
	s_add_i32 s5, s20, s15
	s_waitcnt vmcnt(7)
	ds_write_b128 v160, v[118:121]
	s_waitcnt vmcnt(6)
	ds_write2_b64 v166, v[114:115], v[116:117] offset1:1
	s_waitcnt vmcnt(5)
	ds_write_b128 v160, v[126:129] offset:8704
	s_waitcnt vmcnt(4)
	ds_write2_b64 v167, v[122:123], v[124:125] offset1:1
	s_waitcnt vmcnt(3)
	ds_write_b128 v160, v[134:137] offset:17408
	s_waitcnt vmcnt(2)
	ds_write2_b64 v168, v[130:131], v[132:133] offset1:1
	s_waitcnt vmcnt(1)
	ds_write_b128 v160, v[142:145] offset:26112
	s_waitcnt vmcnt(0)
	ds_write2_b64 v169, v[138:139], v[140:141] offset1:1
	s_waitcnt lgkmcnt(0)
	s_barrier
	global_load_dwordx4 v[118:121], v[66:67], off
	v_lshl_add_u64 v[66:67], s[30:31], 1, v[152:153]
	s_add_i32 s30, s5, s4
	s_add_i32 s4, s4, s15
	global_load_dwordx4 v[114:117], v[66:67], off
	v_add_u32_e32 v66, s4, v164
	s_add_i32 s4, s11, s14
	s_cmp_lt_u32 s4, s7
	v_ashrrev_i32_e32 v67, 31, v66
	s_cselect_b32 s4, 0, s7
	v_lshlrev_b64 v[66:67], 9, v[66:67]
	s_cselect_b32 s5, s24, s1
	s_lshl_b32 s4, s4, 5
	v_lshl_add_u64 v[66:67], v[150:151], 0, v[66:67]
	s_sub_i32 s4, s5, s4
	s_add_i32 s5, s21, s15
	global_load_dwordx4 v[126:129], v[66:67], off
	v_lshl_add_u64 v[66:67], s[30:31], 1, v[152:153]
	s_add_i32 s30, s5, s4
	s_add_i32 s4, s4, s15
	global_load_dwordx4 v[122:125], v[66:67], off
	v_add_u32_e32 v66, s4, v162
	s_add_i32 s4, s18, s14
	s_cmp_lt_u32 s4, s7
	v_ashrrev_i32_e32 v67, 31, v66
	s_cselect_b32 s4, 0, s7
	v_lshlrev_b64 v[66:67], 9, v[66:67]
	s_cselect_b32 s5, s24, s1
	s_lshl_b32 s4, s4, 5
	v_lshl_add_u64 v[66:67], v[150:151], 0, v[66:67]
	s_sub_i32 s4, s5, s4
	s_add_i32 s5, s19, s15
	global_load_dwordx4 v[134:137], v[66:67], off
	v_lshl_add_u64 v[66:67], s[30:31], 1, v[152:153]
	s_add_i32 s30, s5, s4
	s_add_i32 s4, s4, s15
	global_load_dwordx4 v[130:133], v[66:67], off
	v_add_u32_e32 v66, s4, v163
	v_ashrrev_i32_e32 v67, 31, v66
	v_lshlrev_b64 v[66:67], 9, v[66:67]
	v_lshl_add_u64 v[66:67], v[150:151], 0, v[66:67]
	global_load_dwordx4 v[142:145], v[66:67], off
	v_lshl_add_u64 v[66:67], s[30:31], 1, v[152:153]
	global_load_dwordx4 v[138:141], v[66:67], off
	ds_read_b128 v[66:69], v159
	ds_read_b128 v[176:179], v159 offset:32
	s_waitcnt lgkmcnt(1)
	v_mfma_f32_32x32x16_bf16 v[66:81], v[66:69], v[110:113], 0
	v_mov_b32_e32 v0, v149
	v_mov_b32_e32 v175, v148
	s_add_i32 s15, s15, 32
	s_add_i32 s14, s14, 1
	s_cmp_lg_u32 s20, s15
	s_waitcnt lgkmcnt(0)
	v_mfma_f32_32x32x16_bf16 v[66:81], v[176:179], v[106:109], v[66:81]
	ds_read_b128 v[176:179], v159 offset:64
	s_waitcnt lgkmcnt(0)
	v_mfma_f32_32x32x16_bf16 v[66:81], v[176:179], v[102:105], v[66:81]
	ds_read_b128 v[176:179], v159 offset:96
	s_waitcnt lgkmcnt(0)
	v_mfma_f32_32x32x16_bf16 v[66:81], v[176:179], v[98:101], v[66:81]
	ds_read_b128 v[176:179], v159 offset:128
	s_waitcnt lgkmcnt(0)
	v_mfma_f32_32x32x16_bf16 v[66:81], v[176:179], v[94:97], v[66:81]
	ds_read_b128 v[176:179], v159 offset:160
	s_waitcnt lgkmcnt(0)
	v_mfma_f32_32x32x16_bf16 v[66:81], v[176:179], v[90:93], v[66:81]
	ds_read_b128 v[176:179], v159 offset:192
	s_waitcnt lgkmcnt(0)
	v_mfma_f32_32x32x16_bf16 v[66:81], v[176:179], v[86:89], v[66:81]
	ds_read_b128 v[176:179], v159 offset:224
	s_waitcnt lgkmcnt(0)
	v_mfma_f32_32x32x16_bf16 v[66:81], v[176:179], v[82:85], v[66:81]
	s_nop 11
	v_max_f32_e32 v148, v67, v67
	v_max_f32_e32 v149, v66, v66
	v_max_f32_e32 v148, v149, v148
	v_max3_f32 v148, v148, v68, v69
	v_max3_f32 v148, v148, v70, v71
	v_max3_f32 v148, v148, v72, v73
	v_max3_f32 v148, v148, v74, v75
	v_max3_f32 v148, v148, v76, v77
	v_max3_f32 v148, v148, v78, v79
	v_max3_f32 v148, v148, v80, v81
	v_mov_b32_e32 v149, v148
	s_nop 1
	v_permlane32_swap_b32 v149, v148
	s_waitcnt lgkmcnt(0)
	v_max3_f32 v149, v0, v148, v149
	v_mov_b32_e32 v148, v81
	v_pk_mul_f32 v[176:177], v[148:149], s[28:29] op_sel_hi:[1,0]
	v_sub_f32_e32 v0, v0, v149
	v_fma_f32 v70, v70, s28, -v177
	v_exp_f32_e32 v81, v70
	v_fma_f32 v70, v71, s28, -v177
	v_exp_f32_e32 v178, v70
	v_fma_f32 v70, v72, s28, -v177
	v_exp_f32_e32 v179, v70
	v_fma_f32 v70, v73, s28, -v177
	v_exp_f32_e32 v73, v70
	v_fma_f32 v70, v74, s28, -v177
	v_exp_f32_e32 v74, v70
	v_fma_f32 v70, v75, s28, -v177
	v_exp_f32_e32 v75, v70
	v_fma_f32 v70, v76, s28, -v177
	v_fma_f32 v66, v66, s28, -v177
	v_exp_f32_e32 v76, v70
	v_fma_f32 v70, v77, s28, -v177
	v_exp_f32_e32 v66, v66
	v_fma_f32 v67, v67, s28, -v177
	v_exp_f32_e32 v77, v70
	v_fma_f32 v70, v78, s28, -v177
	v_exp_f32_e32 v67, v67
	v_fma_f32 v68, v68, s28, -v177
	v_exp_f32_e32 v78, v70
	v_fma_f32 v70, v79, s28, -v177
	v_exp_f32_e32 v68, v68
	v_fma_f32 v69, v69, s28, -v177
	v_exp_f32_e32 v79, v70
	v_fma_f32 v70, v80, s28, -v177
	v_exp_f32_e32 v69, v69
	v_exp_f32_e32 v80, v70
	v_sub_f32_e32 v70, v176, v177
	v_exp_f32_e32 v176, v70
	v_add_f32_e32 v70, v67, v66
	v_add_f32_e32 v70, v68, v70
	v_add_f32_e32 v70, v69, v70
	v_add_f32_e32 v70, v81, v70
	v_add_f32_e32 v70, v178, v70
	v_add_f32_e32 v70, v179, v70
	v_add_f32_e32 v70, v73, v70
	v_add_f32_e32 v70, v74, v70
	v_add_f32_e32 v70, v75, v70
	v_add_f32_e32 v70, v76, v70
	v_add_f32_e32 v70, v77, v70
	v_add_f32_e32 v70, v78, v70
	v_mul_f32_e32 v0, 0x3e0293ee, v0
	v_add_f32_e32 v70, v79, v70
	v_exp_f32_e32 v0, v0
	v_add_f32_e32 v70, v80, v70
	v_cvt_pk_bf16_f32 v73, v179, v73
	v_add_u32_e32 v179, 0x8800, v165
	v_add_f32_e32 v148, v176, v70
	v_cvt_pk_bf16_f32 v70, v66, v67
	v_cvt_pk_bf16_f32 v71, v68, v69
	v_cvt_pk_bf16_f32 v72, v81, v178
	v_cvt_pk_bf16_f32 v66, v74, v75
	v_cvt_pk_bf16_f32 v67, v76, v77
	v_cvt_pk_bf16_f32 v68, v78, v79
	v_cvt_pk_bf16_f32 v69, v80, v176
	ds_read2_b64 v[74:77], v179 offset1:2
	ds_read2_b64 v[78:81], v179 offset0:4 offset1:6
	v_pk_mul_f32 v[64:65], v[64:65], v[0:1] op_sel_hi:[1,0]
	v_pk_mul_f32 v[62:63], v[62:63], v[0:1] op_sel_hi:[1,0]
	v_pk_mul_f32 v[60:61], v[60:61], v[0:1] op_sel_hi:[1,0]
	v_pk_mul_f32 v[58:59], v[58:59], v[0:1] op_sel_hi:[1,0]
	v_pk_mul_f32 v[56:57], v[56:57], v[0:1] op_sel_hi:[1,0]
	v_pk_mul_f32 v[54:55], v[54:55], v[0:1] op_sel_hi:[1,0]
	v_pk_mul_f32 v[52:53], v[52:53], v[0:1] op_sel_hi:[1,0]
	v_pk_mul_f32 v[50:51], v[50:51], v[0:1] op_sel_hi:[1,0]
	v_add_u32_e32 v176, 0x9000, v165
	v_pk_mul_f32 v[48:49], v[48:49], v[0:1] op_sel_hi:[1,0]
	s_waitcnt lgkmcnt(1)
	v_mfma_f32_32x32x16_bf16 v[50:65], v[74:77], v[70:73], v[50:65]
	ds_read2_b64 v[74:77], v176 offset0:32 offset1:34
	v_mul_f32_e64 v46, v46, v0
	v_mul_f32_e64 v47, v47, v0
	v_mul_f32_e64 v44, v44, v0
	v_mul_f32_e64 v45, v45, v0
	v_pk_mul_f32 v[42:43], v[42:43], v[0:1] op_sel_hi:[1,0]
	v_pk_mul_f32 v[40:41], v[40:41], v[0:1] op_sel_hi:[1,0]
	v_pk_mul_f32 v[38:39], v[38:39], v[0:1] op_sel_hi:[1,0]
	v_pk_mul_f32 v[36:37], v[36:37], v[0:1] op_sel_hi:[1,0]
	v_pk_mul_f32 v[34:35], v[34:35], v[0:1] op_sel_hi:[1,0]
	v_add_u32_e32 v177, 0x9800, v165
	v_pk_mul_f32 v[32:33], v[32:33], v[0:1] op_sel_hi:[1,0]
	s_waitcnt lgkmcnt(0)
	v_mfma_f32_32x32x16_bf16 v[34:49], v[74:77], v[70:73], v[34:49]
	ds_read2_b64 v[74:77], v176 offset0:36 offset1:38
	v_mul_f32_e64 v30, v30, v0
	v_mul_f32_e64 v31, v31, v0
	v_mul_f32_e64 v28, v28, v0
	v_mul_f32_e64 v29, v29, v0
	v_pk_mul_f32 v[26:27], v[26:27], v[0:1] op_sel_hi:[1,0]
	v_pk_mul_f32 v[24:25], v[24:25], v[0:1] op_sel_hi:[1,0]
	v_pk_mul_f32 v[22:23], v[22:23], v[0:1] op_sel_hi:[1,0]
	v_pk_mul_f32 v[20:21], v[20:21], v[0:1] op_sel_hi:[1,0]
	s_waitcnt lgkmcnt(0)
	v_mfma_f32_32x32x16_bf16 v[34:49], v[74:77], v[66:69], v[34:49]
	ds_read2_b64 v[74:77], v177 offset0:64 offset1:66
	v_mul_f32_e64 v18, v18, v0
	v_mul_f32_e64 v19, v19, v0
	v_add_u32_e32 v178, 0xa000, v165
	v_mul_f32_e64 v16, v16, v0
	v_mul_f32_e64 v17, v17, v0
	v_pk_mul_f32 v[14:15], v[14:15], v[0:1] op_sel_hi:[1,0]
	v_pk_mul_f32 v[12:13], v[12:13], v[0:1] op_sel_hi:[1,0]
	v_pk_mul_f32 v[10:11], v[10:11], v[0:1] op_sel_hi:[1,0]
	s_waitcnt lgkmcnt(0)
	v_mfma_f32_32x32x16_bf16 v[18:33], v[74:77], v[70:73], v[18:33]
	ds_read2_b64 v[74:77], v177 offset0:68 offset1:70
	v_mul_f32_e64 v8, v8, v0
	v_mul_f32_e64 v9, v9, v0
	v_mul_f32_e64 v6, v6, v0
	v_mul_f32_e64 v7, v7, v0
	v_pk_mul_f32 v[4:5], v[4:5], v[0:1] op_sel_hi:[1,0]
	v_pk_mul_f32 v[2:3], v[2:3], v[0:1] op_sel_hi:[1,0]
	v_fmac_f32_e32 v148, v175, v0
	s_waitcnt lgkmcnt(0)
	v_mfma_f32_32x32x16_bf16 v[18:33], v[74:77], v[66:69], v[18:33]
	ds_read2_b64 v[74:77], v178 offset0:96 offset1:98
	s_waitcnt lgkmcnt(0)
	v_mfma_f32_32x32x16_bf16 v[2:17], v[74:77], v[70:73], v[2:17]
	ds_read2_b64 v[70:73], v178 offset0:100 offset1:102
	s_waitcnt lgkmcnt(0)
	s_barrier
	v_mfma_f32_32x32x16_bf16 v[50:65], v[78:81], v[66:69], v[50:65]
	v_mfma_f32_32x32x16_bf16 v[2:17], v[70:73], v[66:69], v[2:17]
	s_cbranch_scc1 .LBB0_592
	s_waitcnt vmcnt(7)
	ds_write_b128 v160, v[118:121]
	s_waitcnt vmcnt(6)
	ds_write2_b64 v166, v[114:115], v[116:117] offset1:1
	s_waitcnt vmcnt(5)
	ds_write_b128 v160, v[126:129] offset:8704
	s_waitcnt vmcnt(4)
	ds_write2_b64 v167, v[122:123], v[124:125] offset1:1
	s_waitcnt vmcnt(3)
	ds_write_b128 v160, v[134:137] offset:17408
	s_waitcnt vmcnt(2)
	ds_write2_b64 v168, v[130:131], v[132:133] offset1:1
	s_waitcnt vmcnt(1)
	ds_write_b128 v160, v[142:145] offset:26112
	s_waitcnt vmcnt(0)
	ds_write2_b64 v169, v[138:139], v[140:141] offset1:1
	s_waitcnt lgkmcnt(0)
	s_barrier
	ds_read_b128 v[66:69], v159
	ds_read_b128 v[114:117], v159 offset:32
	s_waitcnt lgkmcnt(1)
	v_mfma_f32_32x32x16_bf16 v[66:81], v[66:69], v[110:113], 0
	v_readlane_b32 s1, v253, 17
	s_mov_b32 s4, 0xf149f2ca
	s_waitcnt lgkmcnt(0)
	v_mfma_f32_32x32x16_bf16 v[66:81], v[114:117], v[106:109], v[66:81]
	ds_read_b128 v[106:109], v159 offset:64
	ds_read_b128 v[110:113], v159 offset:96
	s_waitcnt lgkmcnt(1)
	v_mfma_f32_32x32x16_bf16 v[66:81], v[106:109], v[102:105], v[66:81]
	s_waitcnt lgkmcnt(0)
	v_mfma_f32_32x32x16_bf16 v[66:81], v[110:113], v[98:101], v[66:81]
	ds_read_b128 v[98:101], v159 offset:128
	ds_read_b128 v[102:105], v159 offset:160
	s_waitcnt lgkmcnt(1)
	v_mfma_f32_32x32x16_bf16 v[66:81], v[98:101], v[94:97], v[66:81]
	v_ashrrev_i32_e32 v100, 6, v157
	s_waitcnt lgkmcnt(0)
	v_mfma_f32_32x32x16_bf16 v[66:81], v[102:105], v[90:93], v[66:81]
	ds_read_b128 v[90:93], v159 offset:192
	ds_read_b128 v[94:97], v159 offset:224
	s_waitcnt lgkmcnt(1)
	v_mfma_f32_32x32x16_bf16 v[66:81], v[90:93], v[86:89], v[66:81]
	ds_read2_b64 v[86:89], v179 offset1:2
	s_waitcnt lgkmcnt(1)
	v_mfma_f32_32x32x16_bf16 v[66:81], v[94:97], v[82:85], v[66:81]
	ds_read2_b64 v[90:93], v179 offset0:4 offset1:6
	ds_read2_b64 v[94:97], v176 offset0:32 offset1:34
	s_nop 9
	v_max_f32_e32 v0, v67, v67
	v_max_f32_e32 v82, v66, v66
	v_max_f32_e32 v0, v82, v0
	v_max3_f32 v0, v0, v68, v69
	v_max3_f32 v0, v0, v70, v71
	v_max3_f32 v0, v0, v72, v73
	v_max3_f32 v0, v0, v74, v75
	v_max3_f32 v0, v0, v76, v77
	v_max3_f32 v0, v0, v78, v79
	v_max3_f32 v0, v0, v80, v81
	v_mov_b32_e32 v83, v0
	v_mov_b32_e32 v84, v81
	v_and_b32_e32 v82, 1, v100
	v_permlane32_swap_b32 v83, v0
	s_waitcnt lgkmcnt(0)
	v_max3_f32 v85, v149, v0, v83
	v_sub_f32_e32 v0, v149, v85
	v_pk_mul_f32 v[98:99], v[84:85], s[28:29] op_sel_hi:[1,0]
	v_mul_f32_e32 v0, 0x3e0293ee, v0
	v_fma_f32 v66, v66, s28, -v99
	v_fma_f32 v67, v67, s28, -v99
	v_fma_f32 v68, v68, s28, -v99
	v_fma_f32 v69, v69, s28, -v99
	v_fma_f32 v70, v70, s28, -v99
	v_fma_f32 v71, v71, s28, -v99
	v_fma_f32 v72, v72, s28, -v99
	v_fma_f32 v73, v73, s28, -v99
	v_fma_f32 v74, v74, s28, -v99
	v_fma_f32 v75, v75, s28, -v99
	v_fma_f32 v76, v76, s28, -v99
	v_fma_f32 v77, v77, s28, -v99
	v_fma_f32 v78, v78, s28, -v99
	v_fma_f32 v79, v79, s28, -v99
	v_fma_f32 v80, v80, s28, -v99
	v_sub_f32_e32 v81, v98, v99
	v_exp_f32_e32 v0, v0
	v_exp_f32_e32 v83, v66
	v_exp_f32_e32 v84, v67
	v_exp_f32_e32 v98, v68
	v_exp_f32_e32 v99, v69
	v_exp_f32_e32 v101, v70
	v_exp_f32_e32 v102, v71
	v_exp_f32_e32 v103, v72
	v_exp_f32_e32 v104, v73
	v_exp_f32_e32 v105, v74
	v_exp_f32_e32 v106, v75
	v_exp_f32_e32 v107, v76
	v_exp_f32_e32 v108, v77
	v_pk_mul_f32 v[48:49], v[48:49], v[0:1] op_sel_hi:[1,0]
	v_pk_mul_f32 v[46:47], v[46:47], v[0:1] op_sel_hi:[1,0]
	v_cvt_pk_bf16_f32 v66, v83, v84
	v_cvt_pk_bf16_f32 v67, v98, v99
	v_cvt_pk_bf16_f32 v68, v101, v102
	v_cvt_pk_bf16_f32 v69, v103, v104
	v_pk_mul_f32 v[44:45], v[44:45], v[0:1] op_sel_hi:[1,0]
	v_pk_mul_f32 v[42:43], v[42:43], v[0:1] op_sel_hi:[1,0]
	v_pk_mul_f32 v[40:41], v[40:41], v[0:1] op_sel_hi:[1,0]
	v_pk_mul_f32 v[38:39], v[38:39], v[0:1] op_sel_hi:[1,0]
	v_pk_mul_f32 v[36:37], v[36:37], v[0:1] op_sel_hi:[1,0]
	v_pk_mul_f32 v[34:35], v[34:35], v[0:1] op_sel_hi:[1,0]
	ds_read2_b64 v[74:77], v176 offset0:36 offset1:38
	v_exp_f32_e32 v109, v78
	v_exp_f32_e32 v110, v79
	v_exp_f32_e32 v111, v80
	v_exp_f32_e32 v112, v81
	v_mfma_f32_32x32x16_bf16 v[34:49], v[94:97], v[66:69], v[34:49]
	ds_read2_b64 v[78:81], v177 offset0:64 offset1:66
	v_cvt_pk_bf16_f32 v70, v105, v106
	v_cvt_pk_bf16_f32 v71, v107, v108
	v_cvt_pk_bf16_f32 v72, v109, v110
	v_cvt_pk_bf16_f32 v73, v111, v112
	v_pk_mul_f32 v[32:33], v[32:33], v[0:1] op_sel_hi:[1,0]
	v_pk_mul_f32 v[30:31], v[30:31], v[0:1] op_sel_hi:[1,0]
	v_pk_mul_f32 v[28:29], v[28:29], v[0:1] op_sel_hi:[1,0]
	v_pk_mul_f32 v[26:27], v[26:27], v[0:1] op_sel_hi:[1,0]
	v_pk_mul_f32 v[24:25], v[24:25], v[0:1] op_sel_hi:[1,0]
	v_pk_mul_f32 v[22:23], v[22:23], v[0:1] op_sel_hi:[1,0]
	v_pk_mul_f32 v[20:21], v[20:21], v[0:1] op_sel_hi:[1,0]
	v_pk_mul_f32 v[18:19], v[18:19], v[0:1] op_sel_hi:[1,0]
	s_waitcnt lgkmcnt(1)
	v_mfma_f32_32x32x16_bf16 v[34:49], v[74:77], v[70:73], v[34:49]
	ds_read2_b64 v[74:77], v177 offset0:68 offset1:70
	v_mul_f32_e64 v64, v64, v0
	v_mul_f32_e64 v65, v65, v0
	v_mul_f32_e64 v62, v62, v0
	v_mul_f32_e64 v63, v63, v0
	v_pk_mul_f32 v[60:61], v[60:61], v[0:1] op_sel_hi:[1,0]
	v_pk_mul_f32 v[58:59], v[58:59], v[0:1] op_sel_hi:[1,0]
	v_pk_mul_f32 v[56:57], v[56:57], v[0:1] op_sel_hi:[1,0]
	v_pk_mul_f32 v[54:55], v[54:55], v[0:1] op_sel_hi:[1,0]
	s_waitcnt lgkmcnt(1)
	v_mfma_f32_32x32x16_bf16 v[18:33], v[78:81], v[66:69], v[18:33]
	v_add_f32_e32 v78, 0, v83
	v_add_f32_e32 v78, v84, v78
	v_add_f32_e32 v78, v98, v78
	v_add_f32_e32 v78, v99, v78
	v_add_f32_e32 v83, v101, v78
	ds_read2_b64 v[78:81], v178 offset0:96 offset1:98
	v_pk_mul_f32 v[52:53], v[52:53], v[0:1] op_sel_hi:[1,0]
	s_waitcnt lgkmcnt(1)
	v_mfma_f32_32x32x16_bf16 v[18:33], v[74:77], v[70:73], v[18:33]
	v_add_f32_e32 v74, v102, v83
	v_add_f32_e32 v74, v103, v74
	v_add_f32_e32 v74, v104, v74
	v_add_f32_e32 v74, v105, v74
	v_mul_f32_e64 v50, v50, v0
	v_mul_f32_e64 v51, v51, v0
	v_add_f32_e32 v74, v106, v74
	v_pk_mul_f32 v[16:17], v[16:17], v[0:1] op_sel_hi:[1,0]
	v_mfma_f32_32x32x16_bf16 v[50:65], v[86:89], v[66:69], v[50:65]
	v_mul_f32_e64 v14, v14, v0
	v_mul_f32_e64 v15, v15, v0
	v_mul_f32_e64 v12, v12, v0
	v_mul_f32_e64 v13, v13, v0
	v_mul_f32_e64 v10, v10, v0
	v_mul_f32_e64 v11, v11, v0
	v_pk_mul_f32 v[8:9], v[8:9], v[0:1] op_sel_hi:[1,0]
	v_pk_mul_f32 v[6:7], v[6:7], v[0:1] op_sel_hi:[1,0]
	v_pk_mul_f32 v[4:5], v[4:5], v[0:1] op_sel_hi:[1,0]
	v_pk_mul_f32 v[2:3], v[2:3], v[0:1] op_sel_hi:[1,0]
	v_add_f32_e32 v83, v107, v74
	ds_read2_b64 v[74:77], v178 offset0:100 offset1:102
	s_waitcnt lgkmcnt(1)
	v_mfma_f32_32x32x16_bf16 v[2:17], v[78:81], v[66:69], v[2:17]
	v_add_f32_e32 v66, v108, v83
	v_add_f32_e32 v66, v109, v66
	v_add_f32_e32 v66, v110, v66
	v_add_f32_e32 v66, v111, v66
	v_add_f32_e32 v66, v112, v66
	v_fmac_f32_e32 v66, v148, v0
	v_mov_b32_e32 v0, v66
	v_mfma_f32_32x32x16_bf16 v[50:65], v[90:93], v[70:73], v[50:65]
	v_lshlrev_b32_e32 v67, 2, v155
	s_nop 1
	v_permlane32_swap_b32 v0, v66
	s_waitcnt lgkmcnt(0)
	s_barrier
	v_add_f32_e32 v0, v66, v0
	v_lshlrev_b32_e32 v66, 9, v100
	v_add3_u32 v66, s1, v66, v67
	ds_write2st64_b32 v66, v85, v0 offset1:1
	v_lshlrev_b32_e32 v0, 14, v100
	v_add3_u32 v0, 0, v0, v67
	v_mfma_f32_32x32x16_bf16 v[2:17], v[74:77], v[70:73], v[2:17]
	s_nop 1
	ds_write2st64_b32 v0, v50, v51 offset1:1
	ds_write2st64_b32 v0, v52, v53 offset0:2 offset1:3
	ds_write2st64_b32 v0, v54, v55 offset0:4 offset1:5
	ds_write2st64_b32 v0, v56, v57 offset0:6 offset1:7
	ds_write2st64_b32 v0, v58, v59 offset0:8 offset1:9
	ds_write2st64_b32 v0, v60, v61 offset0:10 offset1:11
	ds_write2st64_b32 v0, v62, v63 offset0:12 offset1:13
	ds_write2st64_b32 v0, v64, v65 offset0:14 offset1:15
	ds_write2st64_b32 v0, v34, v35 offset0:16 offset1:17
	ds_write2st64_b32 v0, v36, v37 offset0:18 offset1:19
	ds_write2st64_b32 v0, v38, v39 offset0:20 offset1:21
	ds_write2st64_b32 v0, v40, v41 offset0:22 offset1:23
	ds_write2st64_b32 v0, v42, v43 offset0:24 offset1:25
	ds_write2st64_b32 v0, v44, v45 offset0:26 offset1:27
	ds_write2st64_b32 v0, v46, v47 offset0:28 offset1:29
	ds_write2st64_b32 v0, v48, v49 offset0:30 offset1:31
	ds_write2st64_b32 v0, v18, v19 offset0:32 offset1:33
	ds_write2st64_b32 v0, v20, v21 offset0:34 offset1:35
	ds_write2st64_b32 v0, v22, v23 offset0:36 offset1:37
	ds_write2st64_b32 v0, v24, v25 offset0:38 offset1:39
	ds_write2st64_b32 v0, v26, v27 offset0:40 offset1:41
	ds_write2st64_b32 v0, v28, v29 offset0:42 offset1:43
	ds_write2st64_b32 v0, v30, v31 offset0:44 offset1:45
	ds_write2st64_b32 v0, v32, v33 offset0:46 offset1:47
	ds_write2st64_b32 v0, v2, v3 offset0:48 offset1:49
	ds_write2st64_b32 v0, v4, v5 offset0:50 offset1:51
	ds_write2st64_b32 v0, v6, v7 offset0:52 offset1:53
	ds_write2st64_b32 v0, v8, v9 offset0:54 offset1:55
	ds_write2st64_b32 v0, v10, v11 offset0:56 offset1:57
	ds_write2st64_b32 v0, v12, v13 offset0:58 offset1:59
	ds_write2st64_b32 v0, v14, v15 offset0:60 offset1:61
	ds_write2st64_b32 v0, v16, v17 offset0:62 offset1:63
	v_lshlrev_b32_e32 v0, 9, v82
	v_add3_u32 v0, s1, v0, v67
	s_waitcnt lgkmcnt(0)
	s_barrier
	ds_read2st64_b32 v[4:5], v0 offset1:1
	ds_read2st64_b32 v[6:7], v0 offset0:4 offset1:5
	ds_read2st64_b32 v[8:9], v0 offset0:8 offset1:9
	ds_read2st64_b32 v[10:11], v0 offset0:12 offset1:13
	s_mov_b32 s1, s31
	s_lshl_b64 s[0:1], s[0:1], 11
	s_waitcnt lgkmcnt(2)
	v_max3_f32 v0, v4, s4, v6
	s_add_u32 s4, s80, s0
	s_waitcnt lgkmcnt(0)
	v_max3_f32 v0, v0, v8, v10
	v_sub_f32_e32 v2, v4, v0
	v_mul_f32_e32 v2, 0x3e0293ee, v2
	v_exp_f32_e32 v3, v2
	v_sub_f32_e32 v2, v6, v0
	v_mul_f32_e32 v2, 0x3e0293ee, v2
	v_exp_f32_e32 v2, v2
	v_mov_b32_e32 v4, v7
	s_addc_u32 s5, s81, s1
	v_pk_mul_f32 v[6:7], v[4:5], v[2:3]
	v_sub_f32_e32 v4, v8, v0
	v_sub_f32_e32 v0, v10, v0
	v_mul_f32_e32 v4, 0x3e0293ee, v4
	v_mul_f32_e32 v0, 0x3e0293ee, v0
	v_exp_f32_e32 v5, v4
	v_exp_f32_e32 v4, v0
	v_add_f32_e32 v0, 0, v7
	v_mov_b32_e32 v8, v11
	v_add_f32_e32 v0, v6, v0
	v_pk_mul_f32 v[6:7], v[8:9], v[4:5]
	s_nop 0
	v_add_f32_e32 v0, v7, v0
	v_add_f32_e32 v0, v6, v0
	v_div_scale_f32 v6, s[0:1], v0, v0, 1.0
	v_rcp_f32_e32 v7, v6
	s_lshl_b32 s0, s6, 1
	s_add_u32 s0, s4, s0
	s_addc_u32 s1, s5, 0
	v_fma_f32 v8, -v6, v7, 1.0
	v_fmac_f32_e32 v7, v8, v7
	v_div_scale_f32 v8, vcc, 1.0, v0, 1.0
	v_mul_f32_e32 v9, v8, v7
	v_fma_f32 v10, -v6, v9, v8
	v_fmac_f32_e32 v9, v10, v7
	v_fma_f32 v6, -v6, v9, v8
	v_div_fmas_f32 v6, v6, v7, v9
	v_div_fixup_f32 v0, v6, v0, 1.0
	v_lshl_add_u32 v6, v82, 14, 0
	v_lshlrev_b32_e32 v7, 12, v154
	v_add3_u32 v7, v6, v7, v67
	ds_read2st64_b32 v[8:9], v7 offset1:1
	ds_read2st64_b32 v[10:11], v7 offset0:128 offset1:129
	v_mov_b32_e32 v6, v3
	v_add_u32_e32 v24, 0x10000, v7
	v_add_u32_e32 v25, 0x18000, v7
	v_add_u32_e32 v27, 0x10100, v7
	v_add_u32_e32 v28, 0x18100, v7
	ds_read2st64_b32 v[12:13], v7 offset0:2 offset1:3
	ds_read2st64_b32 v[14:15], v7 offset0:4 offset1:5
	ds_read2st64_b32 v[16:17], v7 offset0:6 offset1:7
	s_waitcnt lgkmcnt(4)
	v_pk_fma_f32 v[8:9], v[8:9], v[6:7], 0 op_sel_hi:[1,0,0]
	v_add_u32_e32 v31, 0x18300, v7
	ds_read2st64_b32 v[18:19], v7 offset0:130 offset1:131
	ds_read2st64_b32 v[20:21], v7 offset0:132 offset1:133
	ds_read2st64_b32 v[22:23], v7 offset0:134 offset1:135
	s_waitcnt lgkmcnt(6)
	v_pk_fma_f32 v[8:9], v[10:11], v[2:3], v[8:9] op_sel_hi:[1,0,1]
	v_mov_b32_e32 v10, v5
	v_add_u32_e32 v3, 0x10200, v7
	v_add_u32_e32 v5, 0x18200, v7
	v_add_u32_e32 v11, 0x10300, v7
	ds_read_b32 v24, v24
	ds_read_b32 v26, v25
	ds_read_b32 v25, v27
	ds_read_b32 v27, v28
	ds_read_b32 v28, v3
	ds_read_b32 v30, v5
	ds_read_b32 v29, v11
	ds_read_b32 v31, v31
	s_waitcnt lgkmcnt(13)
	v_pk_fma_f32 v[12:13], v[6:7], v[12:13], 0 op_sel_hi:[0,1,0]
	s_waitcnt lgkmcnt(5)
	v_pk_fma_f32 v[8:9], v[10:11], v[24:25], v[8:9] op_sel_hi:[0,1,1]
	v_pk_fma_f32 v[12:13], v[2:3], v[18:19], v[12:13] op_sel_hi:[0,1,1]
	v_add_u32_e32 v3, 0x10400, v7
	v_pk_fma_f32 v[14:15], v[6:7], v[14:15], 0 op_sel_hi:[0,1,0]
	s_waitcnt lgkmcnt(4)
	v_pk_fma_f32 v[8:9], v[4:5], v[26:27], v[8:9] op_sel_hi:[0,1,1]
	s_waitcnt lgkmcnt(1)
	v_pk_fma_f32 v[12:13], v[10:11], v[28:29], v[12:13] op_sel_hi:[0,1,1]
	v_add_u32_e32 v11, 0x10500, v7
	v_add_u32_e32 v24, 0x18500, v7
	v_pk_fma_f32 v[14:15], v[2:3], v[20:21], v[14:15] op_sel_hi:[0,1,1]
	v_add_u32_e32 v25, 0x10600, v7
	v_add_u32_e32 v26, 0x18600, v7
	v_add_u32_e32 v27, 0x10700, v7
	s_waitcnt lgkmcnt(0)
	v_pk_fma_f32 v[12:13], v[4:5], v[30:31], v[12:13] op_sel_hi:[0,1,1]
	v_add_u32_e32 v5, 0x18400, v7
	v_add_u32_e32 v28, 0x18700, v7
	ds_read_b32 v18, v3
	ds_read_b32 v20, v5
	ds_read_b32 v19, v11
	ds_read_b32 v21, v24
	ds_read_b32 v24, v25
	ds_read_b32 v26, v26
	ds_read_b32 v25, v27
	ds_read_b32 v27, v28
	s_waitcnt lgkmcnt(5)
	v_pk_fma_f32 v[14:15], v[10:11], v[18:19], v[14:15] op_sel_hi:[0,1,1]
	s_waitcnt lgkmcnt(4)
	v_pk_fma_f32 v[14:15], v[4:5], v[20:21], v[14:15] op_sel_hi:[0,1,1]
	ds_read2st64_b32 v[18:19], v7 offset0:8 offset1:9
	ds_read2st64_b32 v[20:21], v7 offset0:136 offset1:137
	v_pk_fma_f32 v[16:17], v[6:7], v[16:17], 0 op_sel_hi:[0,1,0]
	v_pk_fma_f32 v[16:17], v[2:3], v[22:23], v[16:17] op_sel_hi:[0,1,1]
	s_waitcnt lgkmcnt(3)
	v_pk_fma_f32 v[16:17], v[10:11], v[24:25], v[16:17] op_sel_hi:[0,1,1]
	s_waitcnt lgkmcnt(2)
	v_pk_fma_f32 v[16:17], v[4:5], v[26:27], v[16:17] op_sel_hi:[0,1,1]
	v_add_u32_e32 v3, 0x10800, v7
	v_add_u32_e32 v35, 0x18900, v7
	ds_read2st64_b32 v[22:23], v7 offset0:10 offset1:11
	ds_read2st64_b32 v[24:25], v7 offset0:12 offset1:13
	ds_read2st64_b32 v[26:27], v7 offset0:14 offset1:15
	s_waitcnt lgkmcnt(4)
	v_pk_fma_f32 v[18:19], v[6:7], v[18:19], 0 op_sel_hi:[0,1,0]
	v_add_u32_e32 v36, 0x10a00, v7
	v_add_u32_e32 v37, 0x18a00, v7
	v_add_u32_e32 v39, 0x10b00, v7
	v_add_u32_e32 v5, 0x18800, v7
	v_add_u32_e32 v11, 0x10900, v7
	ds_read2st64_b32 v[28:29], v7 offset0:138 offset1:139
	ds_read2st64_b32 v[30:31], v7 offset0:140 offset1:141
	ds_read2st64_b32 v[32:33], v7 offset0:142 offset1:143
	s_waitcnt lgkmcnt(6)
	v_pk_fma_f32 v[18:19], v[2:3], v[20:21], v[18:19] op_sel_hi:[0,1,1]
	v_add_u32_e32 v40, 0x18b00, v7
	ds_read_b32 v20, v3
	ds_read_b32 v34, v5
	ds_read_b32 v21, v11
	ds_read_b32 v35, v35
	ds_read_b32 v36, v36
	ds_read_b32 v38, v37
	ds_read_b32 v37, v39
	ds_read_b32 v39, v40
	s_waitcnt lgkmcnt(5)
	v_pk_fma_f32 v[18:19], v[10:11], v[20:21], v[18:19] op_sel_hi:[0,1,1]
	v_pk_fma_f32 v[20:21], v[6:7], v[22:23], 0 op_sel_hi:[0,1,0]
	v_pk_fma_f32 v[20:21], v[2:3], v[28:29], v[20:21] op_sel_hi:[0,1,1]
	v_add_u32_e32 v3, 0x10c00, v7
	v_pk_fma_f32 v[22:23], v[6:7], v[24:25], 0 op_sel_hi:[0,1,0]
	s_waitcnt lgkmcnt(4)
	v_pk_fma_f32 v[18:19], v[4:5], v[34:35], v[18:19] op_sel_hi:[0,1,1]
	s_waitcnt lgkmcnt(1)
	v_pk_fma_f32 v[20:21], v[10:11], v[36:37], v[20:21] op_sel_hi:[0,1,1]
	v_add_u32_e32 v29, 0x18d00, v7
	v_pk_fma_f32 v[22:23], v[2:3], v[30:31], v[22:23] op_sel_hi:[0,1,1]
	v_add_u32_e32 v30, 0x10e00, v7
	v_add_u32_e32 v31, 0x18e00, v7
	v_add_u32_e32 v35, 0x10f00, v7
	s_waitcnt lgkmcnt(0)
	v_pk_fma_f32 v[20:21], v[4:5], v[38:39], v[20:21] op_sel_hi:[0,1,1]
	v_add_u32_e32 v5, 0x18c00, v7
	v_add_u32_e32 v11, 0x10d00, v7
	v_add_u32_e32 v7, 0x18f00, v7
	ds_read_b32 v24, v3
	ds_read_b32 v28, v5
	ds_read_b32 v25, v11
	ds_read_b32 v29, v29
	ds_read_b32 v30, v30
	ds_read_b32 v34, v31
	ds_read_b32 v31, v35
	ds_read_b32 v35, v7
	v_pk_fma_f32 v[6:7], v[6:7], v[26:27], 0 op_sel_hi:[0,1,0]
	v_pk_fma_f32 v[2:3], v[2:3], v[32:33], v[6:7] op_sel_hi:[0,1,1]
	s_waitcnt lgkmcnt(5)
	v_pk_fma_f32 v[22:23], v[10:11], v[24:25], v[22:23] op_sel_hi:[0,1,1]
	s_waitcnt lgkmcnt(1)
	v_pk_fma_f32 v[2:3], v[10:11], v[30:31], v[2:3] op_sel_hi:[0,1,1]
	v_pk_fma_f32 v[22:23], v[4:5], v[28:29], v[22:23] op_sel_hi:[0,1,1]
	s_waitcnt lgkmcnt(0)
	v_pk_fma_f32 v[2:3], v[4:5], v[34:35], v[2:3] op_sel_hi:[0,1,1]
	v_pk_mul_f32 v[8:9], v[8:9], v[0:1] op_sel_hi:[1,0]
	v_pk_mul_f32 v[12:13], v[0:1], v[12:13] op_sel_hi:[0,1]
	v_pk_mul_f32 v[14:15], v[0:1], v[14:15] op_sel_hi:[0,1]
	v_pk_mul_f32 v[16:17], v[0:1], v[16:17] op_sel_hi:[0,1]
	v_pk_mul_f32 v[18:19], v[0:1], v[18:19] op_sel_hi:[0,1]
	v_pk_mul_f32 v[20:21], v[0:1], v[20:21] op_sel_hi:[0,1]
	v_pk_mul_f32 v[22:23], v[0:1], v[22:23] op_sel_hi:[0,1]
	v_pk_mul_f32 v[2:3], v[0:1], v[2:3] op_sel_hi:[0,1]
	v_lshlrev_b32_e32 v0, 11, v147
	v_lshl_or_b32 v0, v82, 16, v0
	v_lshlrev_b32_e32 v6, 5, v154
	v_lshl_add_u64 v[4:5], s[0:1], 0, v[0:1]
	v_ashrrev_i32_e32 v7, 31, v6
	v_lshl_add_u64 v[4:5], v[6:7], 1, v[4:5]
	v_mov_b32_e32 v147, v1
	v_lshl_add_u64 v[4:5], v[4:5], 0, v[146:147]
	s_mov_b64 s[0:1], 0x4328400
	v_lshl_add_u64 v[6:7], v[4:5], 0, s[0:1]
	s_mov_b32 s0, 0x4328000
	v_add_co_u32_e32 v4, vcc, s0, v4
	v_cvt_pk_bf16_f32 v8, v8, v9
	v_cvt_pk_bf16_f32 v9, v12, v13
	v_addc_co_u32_e32 v5, vcc, 0, v5, vcc
	global_store_dwordx2 v[4:5], v[8:9], off offset:1024
	v_cvt_pk_bf16_f32 v4, v14, v15
	v_cvt_pk_bf16_f32 v5, v16, v17
	global_store_dwordx2 v[6:7], v[4:5], off offset:16
	v_cvt_pk_bf16_f32 v4, v18, v19
	v_cvt_pk_bf16_f32 v5, v20, v21
	global_store_dwordx2 v[6:7], v[4:5], off offset:32
	v_cvt_pk_bf16_f32 v4, v22, v23
	v_cvt_pk_bf16_f32 v5, v2, v3
	global_store_dwordx2 v[6:7], v[4:5], off offset:48
	s_barrier
	s_mov_b64 s[0:1], 0
